# runtime-K GEMM loops (down / out projections): LDS-DMA loads issued before the ds_read block in each load segment (more lead for the global loads); on top of v17
# speedup vs baseline: 1.0015x; 1.0015x over previous
; #define PG8_STAGE(bufoff, gbase, voff) do { _Pragma("unroll") for (int _i = 0; _i < 2; ++_i) \
;         __builtin_amdgcn_global_load_lds((const unsigned*)((const char*)(gbase) + (voff)[_i]), (PG8_LAS unsigned*)(lds + (bufoff) + ldsw + _i * 8192), 16, 0, 0); } while (0)
; #define PG8_LDA(dst, b, h) do { _Pragma("unroll") for (int m = 0; m < 4; ++m) _Pragma("unroll") for (int k = 0; k < 2; ++k) dst[m][k] = *(const PG8_LAS bf16x8*)(lds + PG8_SA(b, h) + aoff + m * 2048 + k * 1024); } while (0)
; #define PG8_LDB(dst, b, h) do { _Pragma("unroll") for (int n = 0; n < 2; ++n) _Pragma("unroll") for (int k = 0; k < 2; ++k) dst[n][k] = *(const PG8_LAS bf16x8*)(lds + PG8_SB(b, h) + boff + n * 2048 + k * 1024); } while (0)
; #define PG8_MMA(ai, bj, At, Bt) do { __builtin_amdgcn_s_setprio(1); _Pragma("unroll") for (int m = 0; m < 4; ++m) _Pragma("unroll") for (int n = 0; n < 2; ++n) _Pragma("unroll") for (int k = 0; k < 2; ++k) \
;         acc[ai][bj][m][n] = __builtin_amdgcn_mfma_f32_16x16x32_bf16(Bt[n][k], At[m][k], acc[ai][bj][m][n], 0, 0, 0); __builtin_amdgcn_s_setprio(0); } while (0)
; #define PG8_WAIT_V(n) asm volatile("s_waitcnt vmcnt(" #n ")" ::: "memory")
; #define PG8_WAIT_L(n) asm volatile("s_waitcnt lgkmcnt(" #n ")" ::: "memory")
; #define PG8_BAR __builtin_amdgcn_s_barrier()
; #define PG8_SCHED __builtin_amdgcn_sched_barrier(0)
; template <class Epi, class Sched, bool ALIGN_EPI = false, bool SP2 = false>
; __device__ __forceinline__ void gemm_phase(PG8_LAS unsigned char* lds, const Gemm g, const Sched& S, const Epi& E) {
;     ...
;             PG8_LDB(B0, 0, 0); PG8_LDB(B1, 0, 1); PG8_SCHED; PG8_LDA(At, 0, 0); PG8_STAGE(PG8_SA(1, 1), a1 + hstep, voffA);
;             PG8_WAIT_V(8); PG8_WAIT_L(0); PG8_BAR; PG8_MMA(0, 0, At, B0); PG8_MMA(0, 1, At, B1); PG8_BAR; PG8_SCHED;
;             PG8_LDA(At, 0, 1); PG8_STAGE(PG8_SB(0, 0), b2, voffB); PG8_STAGE(PG8_SB(0, 1), b2 + hstep, voffB); PG8_STAGE(PG8_SA(0, 0), a2, voffA);
;             PG8_WAIT_V(8); PG8_WAIT_L(0); PG8_BAR; PG8_MMA(1, 0, At, B0); PG8_MMA(1, 1, At, B1); PG8_BAR; PG8_SCHED;
.LBB0_369:
	s_add_i32 s92, s46, 2
	s_add_u32 s61, s44, 0x80
	s_addc_u32 s47, s45, 0
	s_add_i32 s72, 0, 0x10000
	s_cmp_eq_u32 s87, s46
	s_cselect_b32 s47, s43, s47
	s_cselect_b32 s46, s42, s61
	s_cselect_b32 s95, s77, s91
	s_cselect_b32 s94, s76, s90
	s_add_i32 s61, 0, 0x14000
	v_lshl_add_u64 v[228:229], s[44:45], 0, v[140:141]
	s_add_i32 m0, s51, 0xc000
	s_nop 0
	global_load_lds_dwordx4 v[228:229], off
	v_lshl_add_u64 v[228:229], s[44:45], 0, v[138:139]
	s_add_i32 m0, s51, 0xe000
	s_nop 0
	global_load_lds_dwordx4 v[228:229], off
	v_add_u32_e32 v149, s72, v146
	ds_read_b128 v[142:145], v149
	ds_read_b128 v[150:153], v149 offset:1024
	ds_read_b128 v[154:157], v149 offset:2048
	ds_read_b128 v[158:161], v149 offset:3072
	v_add_u32_e32 v149, s61, v146
	ds_read_b128 v[170:173], v149
	ds_read_b128 v[174:177], v149 offset:1024
	ds_read_b128 v[178:181], v149 offset:2048
	ds_read_b128 v[182:185], v149 offset:3072
	ds_read_b128 v[196:199], v148
	ds_read_b128 v[200:203], v148 offset:1024
	ds_read_b128 v[204:207], v148 offset:2048
	ds_read_b128 v[208:211], v148 offset:3072
	ds_read_b128 v[212:215], v148 offset:4096
	ds_read_b128 v[216:219], v148 offset:5120
	ds_read_b128 v[220:223], v148 offset:6144
	ds_read_b128 v[224:227], v148 offset:7168
	s_waitcnt vmcnt(8)
	s_waitcnt lgkmcnt(0)
	s_barrier
	v_mfma_f32_16x16x32_bf16 v[126:129], v[142:145], v[196:199], v[126:129]
	v_mfma_f32_16x16x32_bf16 v[122:125], v[154:157], v[196:199], v[122:125]
	v_mfma_f32_16x16x32_bf16 v[110:113], v[142:145], v[204:207], v[110:113]
	v_mfma_f32_16x16x32_bf16 v[106:109], v[154:157], v[204:207], v[106:109]
	v_mfma_f32_16x16x32_bf16 v[94:97], v[142:145], v[212:215], v[94:97]
	v_mfma_f32_16x16x32_bf16 v[90:93], v[154:157], v[212:215], v[90:93]
	v_mfma_f32_16x16x32_bf16 v[78:81], v[142:145], v[220:223], v[78:81]
	v_mfma_f32_16x16x32_bf16 v[74:77], v[154:157], v[220:223], v[74:77]
	v_mfma_f32_16x16x32_bf16 v[126:129], v[150:153], v[200:203], v[126:129]
	v_mfma_f32_16x16x32_bf16 v[122:125], v[158:161], v[200:203], v[122:125]
	v_mfma_f32_16x16x32_bf16 v[110:113], v[150:153], v[208:211], v[110:113]
	v_mfma_f32_16x16x32_bf16 v[106:109], v[158:161], v[208:211], v[106:109]
	v_mfma_f32_16x16x32_bf16 v[94:97], v[150:153], v[216:219], v[94:97]
	v_mfma_f32_16x16x32_bf16 v[90:93], v[158:161], v[216:219], v[90:93]
	v_mfma_f32_16x16x32_bf16 v[78:81], v[150:153], v[224:227], v[78:81]
	v_mfma_f32_16x16x32_bf16 v[74:77], v[158:161], v[224:227], v[74:77]
	v_mfma_f32_16x16x32_bf16 v[118:121], v[170:173], v[196:199], v[118:121]
	v_mfma_f32_16x16x32_bf16 v[114:117], v[178:181], v[196:199], v[114:117]
	v_mfma_f32_16x16x32_bf16 v[102:105], v[170:173], v[204:207], v[102:105]
	v_mfma_f32_16x16x32_bf16 v[98:101], v[178:181], v[204:207], v[98:101]
	v_mfma_f32_16x16x32_bf16 v[86:89], v[170:173], v[212:215], v[86:89]
	v_mfma_f32_16x16x32_bf16 v[82:85], v[178:181], v[212:215], v[82:85]
	v_mfma_f32_16x16x32_bf16 v[70:73], v[170:173], v[220:223], v[70:73]
	v_mfma_f32_16x16x32_bf16 v[66:69], v[178:181], v[220:223], v[66:69]
	v_mfma_f32_16x16x32_bf16 v[118:121], v[174:177], v[200:203], v[118:121]
	v_mfma_f32_16x16x32_bf16 v[114:117], v[182:185], v[200:203], v[114:117]
	v_mfma_f32_16x16x32_bf16 v[102:105], v[174:177], v[208:211], v[102:105]
	v_mfma_f32_16x16x32_bf16 v[98:101], v[182:185], v[208:211], v[98:101]
	v_mfma_f32_16x16x32_bf16 v[86:89], v[174:177], v[216:219], v[86:89]
	v_mfma_f32_16x16x32_bf16 v[82:85], v[182:185], v[216:219], v[82:85]
	v_mfma_f32_16x16x32_bf16 v[70:73], v[174:177], v[224:227], v[70:73]
	v_mfma_f32_16x16x32_bf16 v[66:69], v[182:185], v[224:227], v[66:69]
	s_barrier
	s_add_i32 s72, s72, s50
	v_lshl_add_u64 v[228:229], s[94:95], 0, v[132:133]
	s_mov_b32 m0, s72
	s_nop 0
	global_load_lds_dwordx4 v[228:229], off
	s_add_i32 m0, s72, 0x2000
	v_lshl_add_u64 v[230:231], s[94:95], 0, v[136:137]
	s_add_u32 s94, s94, s8
	s_addc_u32 s95, s95, 0
	s_add_i32 s61, s61, s50
	global_load_lds_dwordx4 v[230:231], off
	v_lshl_add_u64 v[232:233], s[94:95], 0, v[132:133]
	s_mov_b32 m0, s61
	v_lshl_add_u64 v[234:235], s[94:95], 0, v[136:137]
	global_load_lds_dwordx4 v[232:233], off
	s_add_i32 m0, s61, 0x2000
	v_lshl_add_u64 v[236:237], s[46:47], 0, v[130:131]
	global_load_lds_dwordx4 v[234:235], off
	s_mov_b32 m0, s51
	v_lshl_add_u64 v[238:239], s[46:47], 0, v[134:135]
	global_load_lds_dwordx4 v[236:237], off
	s_mov_b32 m0, s78
	s_nop 0
	global_load_lds_dwordx4 v[238:239], off
	ds_read_b128 v[196:199], v148 offset:16384
	ds_read_b128 v[200:203], v148 offset:17408
	ds_read_b128 v[204:207], v148 offset:18432
	ds_read_b128 v[208:211], v148 offset:19456
	ds_read_b128 v[212:215], v148 offset:20480
	ds_read_b128 v[216:219], v148 offset:21504
	ds_read_b128 v[220:223], v148 offset:22528
	ds_read_b128 v[224:227], v148 offset:23552
	s_waitcnt vmcnt(8)
	s_waitcnt lgkmcnt(0)
	s_barrier
; #define PG8_STAGE(bufoff, gbase, voff) do { _Pragma("unroll") for (int _i = 0; _i < 2; ++_i) \
;         __builtin_amdgcn_global_load_lds((const unsigned*)((const char*)(gbase) + (voff)[_i]), (PG8_LAS unsigned*)(lds + (bufoff) + ldsw + _i * 8192), 16, 0, 0); } while (0)
; #define PG8_LDA(dst, b, h) do { _Pragma("unroll") for (int m = 0; m < 4; ++m) _Pragma("unroll") for (int k = 0; k < 2; ++k) dst[m][k] = *(const PG8_LAS bf16x8*)(lds + PG8_SA(b, h) + aoff + m * 2048 + k * 1024); } while (0)
; #define PG8_LDB(dst, b, h) do { _Pragma("unroll") for (int n = 0; n < 2; ++n) _Pragma("unroll") for (int k = 0; k < 2; ++k) dst[n][k] = *(const PG8_LAS bf16x8*)(lds + PG8_SB(b, h) + boff + n * 2048 + k * 1024); } while (0)
; #define PG8_MMA(ai, bj, At, Bt) do { __builtin_amdgcn_s_setprio(1); _Pragma("unroll") for (int m = 0; m < 4; ++m) _Pragma("unroll") for (int n = 0; n < 2; ++n) _Pragma("unroll") for (int k = 0; k < 2; ++k) \
;         acc[ai][bj][m][n] = __builtin_amdgcn_mfma_f32_16x16x32_bf16(Bt[n][k], At[m][k], acc[ai][bj][m][n], 0, 0, 0); __builtin_amdgcn_s_setprio(0); } while (0)
; #define PG8_WAIT_V(n) asm volatile("s_waitcnt vmcnt(" #n ")" ::: "memory")
; #define PG8_WAIT_L(n) asm volatile("s_waitcnt lgkmcnt(" #n ")" ::: "memory")
; #define PG8_BAR __builtin_amdgcn_s_barrier()
; #define PG8_SCHED __builtin_amdgcn_sched_barrier(0)
; template <class Epi, class Sched, bool ALIGN_EPI = false, bool SP2 = false>
; __device__ __forceinline__ void gemm_phase(PG8_LAS unsigned char* lds, const Gemm g, const Sched& S, const Epi& E) {
;     ...
;             PG8_WAIT_V(8); PG8_WAIT_L(0); PG8_BAR; PG8_MMA(1, 0, At, B0); PG8_MMA(1, 1, At, B1); PG8_BAR; PG8_SCHED;
;             PG8_LDB(B0, 1, 0); PG8_LDB(B1, 1, 1); PG8_SCHED; PG8_LDA(At, 1, 0); PG8_STAGE(PG8_SA(0, 1), a2 + hstep, voffA);
;             PG8_WAIT_V(8); PG8_WAIT_L(0); PG8_BAR; PG8_MMA(0, 0, At, B0); PG8_MMA(0, 1, At, B1); PG8_BAR; PG8_SCHED;
	v_mfma_f32_16x16x32_bf16 v[62:65], v[142:145], v[196:199], v[62:65]
	v_mfma_f32_16x16x32_bf16 v[58:61], v[154:157], v[196:199], v[58:61]
	v_mfma_f32_16x16x32_bf16 v[46:49], v[142:145], v[204:207], v[46:49]
	v_mfma_f32_16x16x32_bf16 v[42:45], v[154:157], v[204:207], v[42:45]
	v_mfma_f32_16x16x32_bf16 v[28:31], v[142:145], v[212:215], v[28:31]
	v_mfma_f32_16x16x32_bf16 v[24:27], v[154:157], v[212:215], v[24:27]
	v_mfma_f32_16x16x32_bf16 v[12:15], v[142:145], v[220:223], v[12:15]
	v_mfma_f32_16x16x32_bf16 v[8:11], v[154:157], v[220:223], v[8:11]
	v_mfma_f32_16x16x32_bf16 v[62:65], v[150:153], v[200:203], v[62:65]
	v_mfma_f32_16x16x32_bf16 v[58:61], v[158:161], v[200:203], v[58:61]
	v_mfma_f32_16x16x32_bf16 v[46:49], v[150:153], v[208:211], v[46:49]
	v_mfma_f32_16x16x32_bf16 v[42:45], v[158:161], v[208:211], v[42:45]
	v_mfma_f32_16x16x32_bf16 v[28:31], v[150:153], v[216:219], v[28:31]
	v_mfma_f32_16x16x32_bf16 v[24:27], v[158:161], v[216:219], v[24:27]
	v_mfma_f32_16x16x32_bf16 v[12:15], v[150:153], v[224:227], v[12:15]
	v_mfma_f32_16x16x32_bf16 v[8:11], v[158:161], v[224:227], v[8:11]
	v_mfma_f32_16x16x32_bf16 v[54:57], v[170:173], v[196:199], v[54:57]
	v_mfma_f32_16x16x32_bf16 v[50:53], v[178:181], v[196:199], v[50:53]
	v_mfma_f32_16x16x32_bf16 v[38:41], v[170:173], v[204:207], v[38:41]
	v_mfma_f32_16x16x32_bf16 v[34:37], v[178:181], v[204:207], v[34:37]
	v_mfma_f32_16x16x32_bf16 v[20:23], v[170:173], v[212:215], v[20:23]
	v_mfma_f32_16x16x32_bf16 v[16:19], v[178:181], v[212:215], v[16:19]
	v_mfma_f32_16x16x32_bf16 v[4:7], v[170:173], v[220:223], v[4:7]
	v_mfma_f32_16x16x32_bf16 v[0:3], v[178:181], v[220:223], v[0:3]
	v_mfma_f32_16x16x32_bf16 v[54:57], v[174:177], v[200:203], v[54:57]
	v_mfma_f32_16x16x32_bf16 v[50:53], v[182:185], v[200:203], v[50:53]
	v_mfma_f32_16x16x32_bf16 v[38:41], v[174:177], v[208:211], v[38:41]
	v_mfma_f32_16x16x32_bf16 v[34:37], v[182:185], v[208:211], v[34:37]
	v_mfma_f32_16x16x32_bf16 v[20:23], v[174:177], v[216:219], v[20:23]
	v_mfma_f32_16x16x32_bf16 v[16:19], v[182:185], v[216:219], v[16:19]
	v_mfma_f32_16x16x32_bf16 v[4:7], v[174:177], v[224:227], v[4:7]
	v_mfma_f32_16x16x32_bf16 v[0:3], v[182:185], v[224:227], v[0:3]
	s_barrier
	s_add_i32 s61, 0, 0x18000
	s_add_i32 s72, 0, 0x1c000
	s_add_u32 s46, s46, s8
	s_addc_u32 s47, s47, 0
	s_mov_b32 m0, s79
	v_lshl_add_u64 v[240:241], s[46:47], 0, v[130:131]
	global_load_lds_dwordx4 v[240:241], off
	v_lshl_add_u64 v[240:241], s[46:47], 0, v[134:135]
	s_mov_b32 m0, s80
	s_nop 0
	global_load_lds_dwordx4 v[240:241], off
	v_add_u32_e32 v149, s61, v146
	ds_read_b128 v[142:145], v149
	ds_read_b128 v[150:153], v149 offset:1024
	ds_read_b128 v[154:157], v149 offset:2048
	ds_read_b128 v[158:161], v149 offset:3072
	v_add_u32_e32 v149, s72, v146
	ds_read_b128 v[170:173], v149
	ds_read_b128 v[174:177], v149 offset:1024
	ds_read_b128 v[178:181], v149 offset:2048
	ds_read_b128 v[182:185], v149 offset:3072
	ds_read_b128 v[196:199], v148 offset:32768
	ds_read_b128 v[200:203], v148 offset:33792
	ds_read_b128 v[204:207], v148 offset:34816
	ds_read_b128 v[208:211], v148 offset:35840
	ds_read_b128 v[212:215], v148 offset:36864
	ds_read_b128 v[216:219], v148 offset:37888
	ds_read_b128 v[220:223], v148 offset:38912
	ds_read_b128 v[224:227], v148 offset:39936
	s_waitcnt vmcnt(8)
	s_waitcnt lgkmcnt(0)
	s_barrier
	v_mfma_f32_16x16x32_bf16 v[126:129], v[142:145], v[196:199], v[126:129]
	v_mfma_f32_16x16x32_bf16 v[122:125], v[154:157], v[196:199], v[122:125]
	v_mfma_f32_16x16x32_bf16 v[110:113], v[142:145], v[204:207], v[110:113]
	v_mfma_f32_16x16x32_bf16 v[106:109], v[154:157], v[204:207], v[106:109]
	v_mfma_f32_16x16x32_bf16 v[94:97], v[142:145], v[212:215], v[94:97]
	v_mfma_f32_16x16x32_bf16 v[90:93], v[154:157], v[212:215], v[90:93]
	v_mfma_f32_16x16x32_bf16 v[78:81], v[142:145], v[220:223], v[78:81]
	v_mfma_f32_16x16x32_bf16 v[74:77], v[154:157], v[220:223], v[74:77]
	v_mfma_f32_16x16x32_bf16 v[126:129], v[150:153], v[200:203], v[126:129]
	v_mfma_f32_16x16x32_bf16 v[122:125], v[158:161], v[200:203], v[122:125]
	v_mfma_f32_16x16x32_bf16 v[110:113], v[150:153], v[208:211], v[110:113]
	v_mfma_f32_16x16x32_bf16 v[106:109], v[158:161], v[208:211], v[106:109]
	v_mfma_f32_16x16x32_bf16 v[94:97], v[150:153], v[216:219], v[94:97]
	v_mfma_f32_16x16x32_bf16 v[90:93], v[158:161], v[216:219], v[90:93]
	v_mfma_f32_16x16x32_bf16 v[78:81], v[150:153], v[224:227], v[78:81]
	v_mfma_f32_16x16x32_bf16 v[74:77], v[158:161], v[224:227], v[74:77]
	v_mfma_f32_16x16x32_bf16 v[118:121], v[170:173], v[196:199], v[118:121]
	v_mfma_f32_16x16x32_bf16 v[114:117], v[178:181], v[196:199], v[114:117]
	v_mfma_f32_16x16x32_bf16 v[102:105], v[170:173], v[204:207], v[102:105]
	v_mfma_f32_16x16x32_bf16 v[98:101], v[178:181], v[204:207], v[98:101]
	v_mfma_f32_16x16x32_bf16 v[86:89], v[170:173], v[212:215], v[86:89]
	v_mfma_f32_16x16x32_bf16 v[82:85], v[178:181], v[212:215], v[82:85]
	v_mfma_f32_16x16x32_bf16 v[70:73], v[170:173], v[220:223], v[70:73]
	v_mfma_f32_16x16x32_bf16 v[66:69], v[178:181], v[220:223], v[66:69]
	v_mfma_f32_16x16x32_bf16 v[118:121], v[174:177], v[200:203], v[118:121]
	v_mfma_f32_16x16x32_bf16 v[114:117], v[182:185], v[200:203], v[114:117]
	v_mfma_f32_16x16x32_bf16 v[102:105], v[174:177], v[208:211], v[102:105]
	v_mfma_f32_16x16x32_bf16 v[98:101], v[182:185], v[208:211], v[98:101]
	v_mfma_f32_16x16x32_bf16 v[86:89], v[174:177], v[216:219], v[86:89]
	v_mfma_f32_16x16x32_bf16 v[82:85], v[182:185], v[216:219], v[82:85]
	v_mfma_f32_16x16x32_bf16 v[70:73], v[174:177], v[224:227], v[70:73]
	v_mfma_f32_16x16x32_bf16 v[66:69], v[182:185], v[224:227], v[66:69]
	s_barrier
; #define PG8_STAGE(bufoff, gbase, voff) do { _Pragma("unroll") for (int _i = 0; _i < 2; ++_i) \
;         __builtin_amdgcn_global_load_lds((const unsigned*)((const char*)(gbase) + (voff)[_i]), (PG8_LAS unsigned*)(lds + (bufoff) + ldsw + _i * 8192), 16, 0, 0); } while (0)
; #define PG8_LDA(dst, b, h) do { _Pragma("unroll") for (int m = 0; m < 4; ++m) _Pragma("unroll") for (int k = 0; k < 2; ++k) dst[m][k] = *(const PG8_LAS bf16x8*)(lds + PG8_SA(b, h) + aoff + m * 2048 + k * 1024); } while (0)
; #define PG8_MMA(ai, bj, At, Bt) do { __builtin_amdgcn_s_setprio(1); _Pragma("unroll") for (int m = 0; m < 4; ++m) _Pragma("unroll") for (int n = 0; n < 2; ++n) _Pragma("unroll") for (int k = 0; k < 2; ++k) \
;         acc[ai][bj][m][n] = __builtin_amdgcn_mfma_f32_16x16x32_bf16(Bt[n][k], At[m][k], acc[ai][bj][m][n], 0, 0, 0); __builtin_amdgcn_s_setprio(0); } while (0)
; #define PG8_WAIT_V(n) asm volatile("s_waitcnt vmcnt(" #n ")" ::: "memory")
; #define PG8_WAIT_L(n) asm volatile("s_waitcnt lgkmcnt(" #n ")" ::: "memory")
; #define PG8_BAR __builtin_amdgcn_s_barrier()
; #define PG8_SCHED __builtin_amdgcn_sched_barrier(0)
; template <class Epi, class Sched, bool ALIGN_EPI = false, bool SP2 = false>
; __device__ __forceinline__ void gemm_phase(PG8_LAS unsigned char* lds, const Gemm g, const Sched& S, const Epi& E) {
;     ...
;             PG8_LDA(At, 1, 1); PG8_STAGE(PG8_SB(1, 0), b3, voffB); PG8_STAGE(PG8_SB(1, 1), b3 + hstep, voffB); PG8_STAGE(PG8_SA(1, 0), a3, voffA);
;             PG8_WAIT_V(8); PG8_WAIT_L(0); PG8_BAR; PG8_MMA(1, 0, At, B0); PG8_MMA(1, 1, At, B1); PG8_BAR; PG8_SCHED;
;     ...
;         if constexpr (ALIGN_EPI) { if (wr == 0) PG8_BAR; }
	s_add_i32 s46, s61, s50
	v_lshl_add_u64 v[228:229], v[228:229], 0, s[34:35]
	s_mov_b32 m0, s46
	s_nop 0
	global_load_lds_dwordx4 v[228:229], off
	v_lshl_add_u64 v[228:229], v[230:231], 0, s[34:35]
	s_add_i32 m0, s46, 0x2000
	s_add_i32 s46, s72, s50
	global_load_lds_dwordx4 v[228:229], off
	v_lshl_add_u64 v[228:229], v[232:233], 0, s[34:35]
	s_mov_b32 m0, s46
	s_nop 0
	global_load_lds_dwordx4 v[228:229], off
	v_lshl_add_u64 v[228:229], v[234:235], 0, s[34:35]
	s_add_i32 m0, s46, 0x2000
	s_nop 0
	global_load_lds_dwordx4 v[228:229], off
	v_lshl_add_u64 v[228:229], v[236:237], 0, s[34:35]
	s_mov_b32 m0, s85
	s_nop 0
	global_load_lds_dwordx4 v[228:229], off
	v_lshl_add_u64 v[228:229], v[238:239], 0, s[34:35]
	s_mov_b32 m0, s86
	s_nop 0
	global_load_lds_dwordx4 v[228:229], off
	ds_read_b128 v[196:199], v148 offset:49152
	ds_read_b128 v[200:203], v148 offset:50176
	ds_read_b128 v[204:207], v148 offset:51200
	ds_read_b128 v[208:211], v148 offset:52224
	ds_read_b128 v[212:215], v148 offset:53248
	ds_read_b128 v[216:219], v148 offset:54272
	ds_read_b128 v[220:223], v148 offset:55296
	ds_read_b128 v[224:227], v148 offset:56320
	s_waitcnt vmcnt(8)
	s_waitcnt lgkmcnt(0)
	s_barrier
	v_mfma_f32_16x16x32_bf16 v[62:65], v[142:145], v[196:199], v[62:65]
	v_mfma_f32_16x16x32_bf16 v[58:61], v[154:157], v[196:199], v[58:61]
	v_mfma_f32_16x16x32_bf16 v[46:49], v[142:145], v[204:207], v[46:49]
	v_mfma_f32_16x16x32_bf16 v[42:45], v[154:157], v[204:207], v[42:45]
	v_mfma_f32_16x16x32_bf16 v[28:31], v[142:145], v[212:215], v[28:31]
	v_mfma_f32_16x16x32_bf16 v[24:27], v[154:157], v[212:215], v[24:27]
	v_mfma_f32_16x16x32_bf16 v[12:15], v[142:145], v[220:223], v[12:15]
	v_mfma_f32_16x16x32_bf16 v[8:11], v[154:157], v[220:223], v[8:11]
	v_mfma_f32_16x16x32_bf16 v[62:65], v[150:153], v[200:203], v[62:65]
	v_mfma_f32_16x16x32_bf16 v[58:61], v[158:161], v[200:203], v[58:61]
	v_mfma_f32_16x16x32_bf16 v[46:49], v[150:153], v[208:211], v[46:49]
	v_mfma_f32_16x16x32_bf16 v[42:45], v[158:161], v[208:211], v[42:45]
	v_mfma_f32_16x16x32_bf16 v[28:31], v[150:153], v[216:219], v[28:31]
	v_mfma_f32_16x16x32_bf16 v[24:27], v[158:161], v[216:219], v[24:27]
	v_mfma_f32_16x16x32_bf16 v[12:15], v[150:153], v[224:227], v[12:15]
	v_mfma_f32_16x16x32_bf16 v[8:11], v[158:161], v[224:227], v[8:11]
	v_mfma_f32_16x16x32_bf16 v[54:57], v[170:173], v[196:199], v[54:57]
	v_mfma_f32_16x16x32_bf16 v[50:53], v[178:181], v[196:199], v[50:53]
	v_mfma_f32_16x16x32_bf16 v[38:41], v[170:173], v[204:207], v[38:41]
	v_mfma_f32_16x16x32_bf16 v[34:37], v[178:181], v[204:207], v[34:37]
	v_mfma_f32_16x16x32_bf16 v[20:23], v[170:173], v[212:215], v[20:23]
	v_mfma_f32_16x16x32_bf16 v[16:19], v[178:181], v[212:215], v[16:19]
	v_mfma_f32_16x16x32_bf16 v[4:7], v[170:173], v[220:223], v[4:7]
	v_mfma_f32_16x16x32_bf16 v[0:3], v[178:181], v[220:223], v[0:3]
	v_mfma_f32_16x16x32_bf16 v[54:57], v[174:177], v[200:203], v[54:57]
	v_mfma_f32_16x16x32_bf16 v[50:53], v[182:185], v[200:203], v[50:53]
	v_mfma_f32_16x16x32_bf16 v[38:41], v[174:177], v[208:211], v[38:41]
	v_mfma_f32_16x16x32_bf16 v[34:37], v[182:185], v[208:211], v[34:37]
	v_mfma_f32_16x16x32_bf16 v[20:23], v[174:177], v[216:219], v[20:23]
	v_mfma_f32_16x16x32_bf16 v[16:19], v[182:185], v[216:219], v[16:19]
	v_mfma_f32_16x16x32_bf16 v[4:7], v[174:177], v[224:227], v[4:7]
	v_mfma_f32_16x16x32_bf16 v[0:3], v[182:185], v[224:227], v[0:3]
	s_barrier
	s_add_u32 s90, s90, 0x100
	s_addc_u32 s91, s91, 0
	s_add_u32 s44, s44, 0x100
	s_addc_u32 s45, s45, 0
	s_cmp_ge_u32 s92, s82
	s_mov_b32 s46, s92
	s_cbranch_scc0 .LBB0_369
	s_and_b64 vcc, exec, s[40:41]
	s_cbranch_vccz .LBB0_372
	s_barrier

; #define PG8_STAGE(bufoff, gbase, voff) do { _Pragma("unroll") for (int _i = 0; _i < 2; ++_i) \
;         __builtin_amdgcn_global_load_lds((const unsigned*)((const char*)(gbase) + (voff)[_i]), (PG8_LAS unsigned*)(lds + (bufoff) + ldsw + _i * 8192), 16, 0, 0); } while (0)
; #define PG8_LDA(dst, b, h) do { _Pragma("unroll") for (int m = 0; m < 4; ++m) _Pragma("unroll") for (int k = 0; k < 2; ++k) dst[m][k] = *(const PG8_LAS bf16x8*)(lds + PG8_SA(b, h) + aoff + m * 2048 + k * 1024); } while (0)
; #define PG8_LDB(dst, b, h) do { _Pragma("unroll") for (int n = 0; n < 2; ++n) _Pragma("unroll") for (int k = 0; k < 2; ++k) dst[n][k] = *(const PG8_LAS bf16x8*)(lds + PG8_SB(b, h) + boff + n * 2048 + k * 1024); } while (0)
; #define PG8_MMA(ai, bj, At, Bt) do { __builtin_amdgcn_s_setprio(1); _Pragma("unroll") for (int m = 0; m < 4; ++m) _Pragma("unroll") for (int n = 0; n < 2; ++n) _Pragma("unroll") for (int k = 0; k < 2; ++k) \
;         acc[ai][bj][m][n] = __builtin_amdgcn_mfma_f32_16x16x32_bf16(Bt[n][k], At[m][k], acc[ai][bj][m][n], 0, 0, 0); __builtin_amdgcn_s_setprio(0); } while (0)
; #define PG8_WAIT_V(n) asm volatile("s_waitcnt vmcnt(" #n ")" ::: "memory")
; #define PG8_WAIT_L(n) asm volatile("s_waitcnt lgkmcnt(" #n ")" ::: "memory")
; #define PG8_BAR __builtin_amdgcn_s_barrier()
; #define PG8_SCHED __builtin_amdgcn_sched_barrier(0)
; template <class Epi, class Sched, bool ALIGN_EPI = false, bool SP2 = false>
; __device__ __forceinline__ void gemm_phase(PG8_LAS unsigned char* lds, const Gemm g, const Sched& S, const Epi& E) {
;     ...
;             PG8_LDB(B0, 0, 0); PG8_LDB(B1, 0, 1); PG8_SCHED; PG8_LDA(At, 0, 0); PG8_STAGE(PG8_SA(1, 1), a1 + hstep, voffA);
;             PG8_WAIT_V(8); PG8_WAIT_L(0); PG8_BAR; PG8_MMA(0, 0, At, B0); PG8_MMA(0, 1, At, B1); PG8_BAR; PG8_SCHED;
;             PG8_LDA(At, 0, 1); PG8_STAGE(PG8_SB(0, 0), b2, voffB); PG8_STAGE(PG8_SB(0, 1), b2 + hstep, voffB); PG8_STAGE(PG8_SA(0, 0), a2, voffA);
;             PG8_WAIT_V(8); PG8_WAIT_L(0); PG8_BAR; PG8_MMA(1, 0, At, B0); PG8_MMA(1, 1, At, B1); PG8_BAR; PG8_SCHED;
.LBB0_411:
	s_add_i32 vcc_lo, s46, 2
	s_add_u32 s38, s44, 0x80
	s_addc_u32 s39, s45, 0
	s_add_i32 vcc_hi, 0, 0x10000
	s_cmp_eq_u32 s92, s46
	s_cselect_b32 s47, s79, s39
	s_cselect_b32 s46, s78, s38
	s_cselect_b32 s39, s81, s49
	s_cselect_b32 s38, s80, s48
	s_add_i32 s61, 0, 0x14000
	v_lshl_add_u64 v[228:229], s[44:45], 0, v[140:141]
	s_add_i32 m0, s82, 0xc000
	s_nop 0
	global_load_lds_dwordx4 v[228:229], off
	v_lshl_add_u64 v[228:229], s[44:45], 0, v[138:139]
	s_add_i32 m0, s82, 0xe000
	s_nop 0
	global_load_lds_dwordx4 v[228:229], off
	v_add_u32_e32 v149, vcc_hi, v146
	ds_read_b128 v[142:145], v149
	ds_read_b128 v[150:153], v149 offset:1024
	ds_read_b128 v[154:157], v149 offset:2048
	ds_read_b128 v[158:161], v149 offset:3072
	v_add_u32_e32 v149, s61, v146
	ds_read_b128 v[170:173], v149
	ds_read_b128 v[174:177], v149 offset:1024
	ds_read_b128 v[178:181], v149 offset:2048
	ds_read_b128 v[182:185], v149 offset:3072
	ds_read_b128 v[196:199], v148
	ds_read_b128 v[200:203], v148 offset:1024
	ds_read_b128 v[204:207], v148 offset:2048
	ds_read_b128 v[208:211], v148 offset:3072
	ds_read_b128 v[212:215], v148 offset:4096
	ds_read_b128 v[216:219], v148 offset:5120
	ds_read_b128 v[220:223], v148 offset:6144
	ds_read_b128 v[224:227], v148 offset:7168
	s_waitcnt vmcnt(8)
	s_waitcnt lgkmcnt(0)
	s_barrier
	v_mfma_f32_16x16x32_bf16 v[126:129], v[142:145], v[196:199], v[126:129]
	v_mfma_f32_16x16x32_bf16 v[122:125], v[154:157], v[196:199], v[122:125]
	v_mfma_f32_16x16x32_bf16 v[110:113], v[142:145], v[204:207], v[110:113]
	v_mfma_f32_16x16x32_bf16 v[106:109], v[154:157], v[204:207], v[106:109]
	v_mfma_f32_16x16x32_bf16 v[94:97], v[142:145], v[212:215], v[94:97]
	v_mfma_f32_16x16x32_bf16 v[90:93], v[154:157], v[212:215], v[90:93]
	v_mfma_f32_16x16x32_bf16 v[78:81], v[142:145], v[220:223], v[78:81]
	v_mfma_f32_16x16x32_bf16 v[74:77], v[154:157], v[220:223], v[74:77]
	v_mfma_f32_16x16x32_bf16 v[126:129], v[150:153], v[200:203], v[126:129]
	v_mfma_f32_16x16x32_bf16 v[122:125], v[158:161], v[200:203], v[122:125]
	v_mfma_f32_16x16x32_bf16 v[110:113], v[150:153], v[208:211], v[110:113]
	v_mfma_f32_16x16x32_bf16 v[106:109], v[158:161], v[208:211], v[106:109]
	v_mfma_f32_16x16x32_bf16 v[94:97], v[150:153], v[216:219], v[94:97]
	v_mfma_f32_16x16x32_bf16 v[90:93], v[158:161], v[216:219], v[90:93]
	v_mfma_f32_16x16x32_bf16 v[78:81], v[150:153], v[224:227], v[78:81]
	v_mfma_f32_16x16x32_bf16 v[74:77], v[158:161], v[224:227], v[74:77]
	v_mfma_f32_16x16x32_bf16 v[118:121], v[170:173], v[196:199], v[118:121]
	v_mfma_f32_16x16x32_bf16 v[114:117], v[178:181], v[196:199], v[114:117]
	v_mfma_f32_16x16x32_bf16 v[102:105], v[170:173], v[204:207], v[102:105]
	v_mfma_f32_16x16x32_bf16 v[98:101], v[178:181], v[204:207], v[98:101]
	v_mfma_f32_16x16x32_bf16 v[86:89], v[170:173], v[212:215], v[86:89]
	v_mfma_f32_16x16x32_bf16 v[82:85], v[178:181], v[212:215], v[82:85]
	v_mfma_f32_16x16x32_bf16 v[70:73], v[170:173], v[220:223], v[70:73]
	v_mfma_f32_16x16x32_bf16 v[66:69], v[178:181], v[220:223], v[66:69]
	v_mfma_f32_16x16x32_bf16 v[118:121], v[174:177], v[200:203], v[118:121]
	v_mfma_f32_16x16x32_bf16 v[114:117], v[182:185], v[200:203], v[114:117]
	v_mfma_f32_16x16x32_bf16 v[102:105], v[174:177], v[208:211], v[102:105]
	v_mfma_f32_16x16x32_bf16 v[98:101], v[182:185], v[208:211], v[98:101]
	v_mfma_f32_16x16x32_bf16 v[86:89], v[174:177], v[216:219], v[86:89]
	v_mfma_f32_16x16x32_bf16 v[82:85], v[182:185], v[216:219], v[82:85]
	v_mfma_f32_16x16x32_bf16 v[70:73], v[174:177], v[224:227], v[70:73]
	v_mfma_f32_16x16x32_bf16 v[66:69], v[182:185], v[224:227], v[66:69]
	s_barrier
	s_add_i32 vcc_hi, vcc_hi, s51
	v_lshl_add_u64 v[228:229], s[38:39], 0, v[132:133]
	s_mov_b32 m0, vcc_hi
	s_nop 0
	global_load_lds_dwordx4 v[228:229], off
	s_add_i32 m0, vcc_hi, 0x2000
	v_lshl_add_u64 v[230:231], s[38:39], 0, v[136:137]
	s_add_u32 s38, s38, s8
	s_addc_u32 s39, s39, 0
	s_add_i32 s61, s61, s51
	global_load_lds_dwordx4 v[230:231], off
	v_lshl_add_u64 v[232:233], s[38:39], 0, v[132:133]
	s_mov_b32 m0, s61
	v_lshl_add_u64 v[234:235], s[38:39], 0, v[136:137]
	global_load_lds_dwordx4 v[232:233], off
	s_add_i32 m0, s61, 0x2000
	v_lshl_add_u64 v[236:237], s[46:47], 0, v[130:131]
	global_load_lds_dwordx4 v[234:235], off
	s_mov_b32 m0, s82
	v_lshl_add_u64 v[238:239], s[46:47], 0, v[134:135]
	global_load_lds_dwordx4 v[236:237], off
	s_mov_b32 m0, s83
	s_nop 0
	global_load_lds_dwordx4 v[238:239], off
	ds_read_b128 v[196:199], v148 offset:16384
	ds_read_b128 v[200:203], v148 offset:17408
	ds_read_b128 v[204:207], v148 offset:18432
	ds_read_b128 v[208:211], v148 offset:19456
	ds_read_b128 v[212:215], v148 offset:20480
	ds_read_b128 v[216:219], v148 offset:21504
	ds_read_b128 v[220:223], v148 offset:22528
	ds_read_b128 v[224:227], v148 offset:23552
	s_waitcnt vmcnt(8)
	s_waitcnt lgkmcnt(0)
	s_barrier
; #define PG8_STAGE(bufoff, gbase, voff) do { _Pragma("unroll") for (int _i = 0; _i < 2; ++_i) \
;         __builtin_amdgcn_global_load_lds((const unsigned*)((const char*)(gbase) + (voff)[_i]), (PG8_LAS unsigned*)(lds + (bufoff) + ldsw + _i * 8192), 16, 0, 0); } while (0)
; #define PG8_LDA(dst, b, h) do { _Pragma("unroll") for (int m = 0; m < 4; ++m) _Pragma("unroll") for (int k = 0; k < 2; ++k) dst[m][k] = *(const PG8_LAS bf16x8*)(lds + PG8_SA(b, h) + aoff + m * 2048 + k * 1024); } while (0)
; #define PG8_LDB(dst, b, h) do { _Pragma("unroll") for (int n = 0; n < 2; ++n) _Pragma("unroll") for (int k = 0; k < 2; ++k) dst[n][k] = *(const PG8_LAS bf16x8*)(lds + PG8_SB(b, h) + boff + n * 2048 + k * 1024); } while (0)
; #define PG8_MMA(ai, bj, At, Bt) do { __builtin_amdgcn_s_setprio(1); _Pragma("unroll") for (int m = 0; m < 4; ++m) _Pragma("unroll") for (int n = 0; n < 2; ++n) _Pragma("unroll") for (int k = 0; k < 2; ++k) \
;         acc[ai][bj][m][n] = __builtin_amdgcn_mfma_f32_16x16x32_bf16(Bt[n][k], At[m][k], acc[ai][bj][m][n], 0, 0, 0); __builtin_amdgcn_s_setprio(0); } while (0)
; #define PG8_WAIT_V(n) asm volatile("s_waitcnt vmcnt(" #n ")" ::: "memory")
; #define PG8_WAIT_L(n) asm volatile("s_waitcnt lgkmcnt(" #n ")" ::: "memory")
; #define PG8_BAR __builtin_amdgcn_s_barrier()
; #define PG8_SCHED __builtin_amdgcn_sched_barrier(0)
; template <class Epi, class Sched, bool ALIGN_EPI = false, bool SP2 = false>
; __device__ __forceinline__ void gemm_phase(PG8_LAS unsigned char* lds, const Gemm g, const Sched& S, const Epi& E) {
;     ...
;             PG8_WAIT_V(8); PG8_WAIT_L(0); PG8_BAR; PG8_MMA(1, 0, At, B0); PG8_MMA(1, 1, At, B1); PG8_BAR; PG8_SCHED;
;             PG8_LDB(B0, 1, 0); PG8_LDB(B1, 1, 1); PG8_SCHED; PG8_LDA(At, 1, 0); PG8_STAGE(PG8_SA(0, 1), a2 + hstep, voffA);
;             PG8_WAIT_V(8); PG8_WAIT_L(0); PG8_BAR; PG8_MMA(0, 0, At, B0); PG8_MMA(0, 1, At, B1); PG8_BAR; PG8_SCHED;
	v_mfma_f32_16x16x32_bf16 v[62:65], v[142:145], v[196:199], v[62:65]
	v_mfma_f32_16x16x32_bf16 v[58:61], v[154:157], v[196:199], v[58:61]
	v_mfma_f32_16x16x32_bf16 v[46:49], v[142:145], v[204:207], v[46:49]
	v_mfma_f32_16x16x32_bf16 v[42:45], v[154:157], v[204:207], v[42:45]
	v_mfma_f32_16x16x32_bf16 v[28:31], v[142:145], v[212:215], v[28:31]
	v_mfma_f32_16x16x32_bf16 v[24:27], v[154:157], v[212:215], v[24:27]
	v_mfma_f32_16x16x32_bf16 v[12:15], v[142:145], v[220:223], v[12:15]
	v_mfma_f32_16x16x32_bf16 v[8:11], v[154:157], v[220:223], v[8:11]
	v_mfma_f32_16x16x32_bf16 v[62:65], v[150:153], v[200:203], v[62:65]
	v_mfma_f32_16x16x32_bf16 v[58:61], v[158:161], v[200:203], v[58:61]
	v_mfma_f32_16x16x32_bf16 v[46:49], v[150:153], v[208:211], v[46:49]
	v_mfma_f32_16x16x32_bf16 v[42:45], v[158:161], v[208:211], v[42:45]
	v_mfma_f32_16x16x32_bf16 v[28:31], v[150:153], v[216:219], v[28:31]
	v_mfma_f32_16x16x32_bf16 v[24:27], v[158:161], v[216:219], v[24:27]
	v_mfma_f32_16x16x32_bf16 v[12:15], v[150:153], v[224:227], v[12:15]
	v_mfma_f32_16x16x32_bf16 v[8:11], v[158:161], v[224:227], v[8:11]
	v_mfma_f32_16x16x32_bf16 v[54:57], v[170:173], v[196:199], v[54:57]
	v_mfma_f32_16x16x32_bf16 v[50:53], v[178:181], v[196:199], v[50:53]
	v_mfma_f32_16x16x32_bf16 v[38:41], v[170:173], v[204:207], v[38:41]
	v_mfma_f32_16x16x32_bf16 v[34:37], v[178:181], v[204:207], v[34:37]
	v_mfma_f32_16x16x32_bf16 v[20:23], v[170:173], v[212:215], v[20:23]
	v_mfma_f32_16x16x32_bf16 v[16:19], v[178:181], v[212:215], v[16:19]
	v_mfma_f32_16x16x32_bf16 v[4:7], v[170:173], v[220:223], v[4:7]
	v_mfma_f32_16x16x32_bf16 v[0:3], v[178:181], v[220:223], v[0:3]
	v_mfma_f32_16x16x32_bf16 v[54:57], v[174:177], v[200:203], v[54:57]
	v_mfma_f32_16x16x32_bf16 v[50:53], v[182:185], v[200:203], v[50:53]
	v_mfma_f32_16x16x32_bf16 v[38:41], v[174:177], v[208:211], v[38:41]
	v_mfma_f32_16x16x32_bf16 v[34:37], v[182:185], v[208:211], v[34:37]
	v_mfma_f32_16x16x32_bf16 v[20:23], v[174:177], v[216:219], v[20:23]
	v_mfma_f32_16x16x32_bf16 v[16:19], v[182:185], v[216:219], v[16:19]
	v_mfma_f32_16x16x32_bf16 v[4:7], v[174:177], v[224:227], v[4:7]
	v_mfma_f32_16x16x32_bf16 v[0:3], v[182:185], v[224:227], v[0:3]
	s_barrier
	s_add_i32 s61, 0, 0x18000
	s_add_i32 vcc_hi, 0, 0x1c000
	s_add_u32 s38, s46, s8
	s_addc_u32 s39, s47, 0
	s_mov_b32 m0, s87
	v_lshl_add_u64 v[240:241], s[38:39], 0, v[130:131]
	global_load_lds_dwordx4 v[240:241], off
	v_lshl_add_u64 v[240:241], s[38:39], 0, v[134:135]
	s_mov_b32 m0, s88
	s_nop 0
	global_load_lds_dwordx4 v[240:241], off
	v_add_u32_e32 v149, s61, v146
	ds_read_b128 v[142:145], v149
	ds_read_b128 v[150:153], v149 offset:1024
	ds_read_b128 v[154:157], v149 offset:2048
	ds_read_b128 v[158:161], v149 offset:3072
	v_add_u32_e32 v149, vcc_hi, v146
	ds_read_b128 v[170:173], v149
	ds_read_b128 v[174:177], v149 offset:1024
	ds_read_b128 v[178:181], v149 offset:2048
	ds_read_b128 v[182:185], v149 offset:3072
	ds_read_b128 v[196:199], v148 offset:32768
	ds_read_b128 v[200:203], v148 offset:33792
	ds_read_b128 v[204:207], v148 offset:34816
	ds_read_b128 v[208:211], v148 offset:35840
	ds_read_b128 v[212:215], v148 offset:36864
	ds_read_b128 v[216:219], v148 offset:37888
	ds_read_b128 v[220:223], v148 offset:38912
	ds_read_b128 v[224:227], v148 offset:39936
	s_waitcnt vmcnt(8)
	s_waitcnt lgkmcnt(0)
	s_barrier
	v_mfma_f32_16x16x32_bf16 v[126:129], v[142:145], v[196:199], v[126:129]
	v_mfma_f32_16x16x32_bf16 v[122:125], v[154:157], v[196:199], v[122:125]
	v_mfma_f32_16x16x32_bf16 v[110:113], v[142:145], v[204:207], v[110:113]
	v_mfma_f32_16x16x32_bf16 v[106:109], v[154:157], v[204:207], v[106:109]
	v_mfma_f32_16x16x32_bf16 v[94:97], v[142:145], v[212:215], v[94:97]
	v_mfma_f32_16x16x32_bf16 v[90:93], v[154:157], v[212:215], v[90:93]
	v_mfma_f32_16x16x32_bf16 v[78:81], v[142:145], v[220:223], v[78:81]
	v_mfma_f32_16x16x32_bf16 v[74:77], v[154:157], v[220:223], v[74:77]
	v_mfma_f32_16x16x32_bf16 v[126:129], v[150:153], v[200:203], v[126:129]
	v_mfma_f32_16x16x32_bf16 v[122:125], v[158:161], v[200:203], v[122:125]
	v_mfma_f32_16x16x32_bf16 v[110:113], v[150:153], v[208:211], v[110:113]
	v_mfma_f32_16x16x32_bf16 v[106:109], v[158:161], v[208:211], v[106:109]
	v_mfma_f32_16x16x32_bf16 v[94:97], v[150:153], v[216:219], v[94:97]
	v_mfma_f32_16x16x32_bf16 v[90:93], v[158:161], v[216:219], v[90:93]
	v_mfma_f32_16x16x32_bf16 v[78:81], v[150:153], v[224:227], v[78:81]
	v_mfma_f32_16x16x32_bf16 v[74:77], v[158:161], v[224:227], v[74:77]
	v_mfma_f32_16x16x32_bf16 v[118:121], v[170:173], v[196:199], v[118:121]
	v_mfma_f32_16x16x32_bf16 v[114:117], v[178:181], v[196:199], v[114:117]
	v_mfma_f32_16x16x32_bf16 v[102:105], v[170:173], v[204:207], v[102:105]
	v_mfma_f32_16x16x32_bf16 v[98:101], v[178:181], v[204:207], v[98:101]
	v_mfma_f32_16x16x32_bf16 v[86:89], v[170:173], v[212:215], v[86:89]
	v_mfma_f32_16x16x32_bf16 v[82:85], v[178:181], v[212:215], v[82:85]
	v_mfma_f32_16x16x32_bf16 v[70:73], v[170:173], v[220:223], v[70:73]
	v_mfma_f32_16x16x32_bf16 v[66:69], v[178:181], v[220:223], v[66:69]
	v_mfma_f32_16x16x32_bf16 v[118:121], v[174:177], v[200:203], v[118:121]
	v_mfma_f32_16x16x32_bf16 v[114:117], v[182:185], v[200:203], v[114:117]
	v_mfma_f32_16x16x32_bf16 v[102:105], v[174:177], v[208:211], v[102:105]
	v_mfma_f32_16x16x32_bf16 v[98:101], v[182:185], v[208:211], v[98:101]
	v_mfma_f32_16x16x32_bf16 v[86:89], v[174:177], v[216:219], v[86:89]
	v_mfma_f32_16x16x32_bf16 v[82:85], v[182:185], v[216:219], v[82:85]
	v_mfma_f32_16x16x32_bf16 v[70:73], v[174:177], v[224:227], v[70:73]
	v_mfma_f32_16x16x32_bf16 v[66:69], v[182:185], v[224:227], v[66:69]
	s_barrier
; #define PG8_STAGE(bufoff, gbase, voff) do { _Pragma("unroll") for (int _i = 0; _i < 2; ++_i) \
;         __builtin_amdgcn_global_load_lds((const unsigned*)((const char*)(gbase) + (voff)[_i]), (PG8_LAS unsigned*)(lds + (bufoff) + ldsw + _i * 8192), 16, 0, 0); } while (0)
; #define PG8_LDA(dst, b, h) do { _Pragma("unroll") for (int m = 0; m < 4; ++m) _Pragma("unroll") for (int k = 0; k < 2; ++k) dst[m][k] = *(const PG8_LAS bf16x8*)(lds + PG8_SA(b, h) + aoff + m * 2048 + k * 1024); } while (0)
; #define PG8_MMA(ai, bj, At, Bt) do { __builtin_amdgcn_s_setprio(1); _Pragma("unroll") for (int m = 0; m < 4; ++m) _Pragma("unroll") for (int n = 0; n < 2; ++n) _Pragma("unroll") for (int k = 0; k < 2; ++k) \
;         acc[ai][bj][m][n] = __builtin_amdgcn_mfma_f32_16x16x32_bf16(Bt[n][k], At[m][k], acc[ai][bj][m][n], 0, 0, 0); __builtin_amdgcn_s_setprio(0); } while (0)
; #define PG8_WAIT_V(n) asm volatile("s_waitcnt vmcnt(" #n ")" ::: "memory")
; #define PG8_WAIT_L(n) asm volatile("s_waitcnt lgkmcnt(" #n ")" ::: "memory")
; #define PG8_BAR __builtin_amdgcn_s_barrier()
; #define PG8_SCHED __builtin_amdgcn_sched_barrier(0)
; template <class Epi, class Sched, bool ALIGN_EPI = false, bool SP2 = false>
; __device__ __forceinline__ void gemm_phase(PG8_LAS unsigned char* lds, const Gemm g, const Sched& S, const Epi& E) {
;     ...
;             PG8_LDA(At, 1, 1); PG8_STAGE(PG8_SB(1, 0), b3, voffB); PG8_STAGE(PG8_SB(1, 1), b3 + hstep, voffB); PG8_STAGE(PG8_SA(1, 0), a3, voffA);
;             PG8_WAIT_V(8); PG8_WAIT_L(0); PG8_BAR; PG8_MMA(1, 0, At, B0); PG8_MMA(1, 1, At, B1); PG8_BAR; PG8_SCHED;
;     ...
;         if constexpr (ALIGN_EPI) { if (wr == 0) PG8_BAR; }
	s_add_i32 s38, s61, s51
	v_lshl_add_u64 v[228:229], v[228:229], 0, s[34:35]
	s_mov_b32 m0, s38
	s_nop 0
	global_load_lds_dwordx4 v[228:229], off
	v_lshl_add_u64 v[228:229], v[230:231], 0, s[34:35]
	s_add_i32 m0, s38, 0x2000
	s_add_i32 s38, vcc_hi, s51
	global_load_lds_dwordx4 v[228:229], off
	v_lshl_add_u64 v[228:229], v[232:233], 0, s[34:35]
	s_mov_b32 m0, s38
	s_nop 0
	global_load_lds_dwordx4 v[228:229], off
	v_lshl_add_u64 v[228:229], v[234:235], 0, s[34:35]
	s_add_i32 m0, s38, 0x2000
	s_nop 0
	global_load_lds_dwordx4 v[228:229], off
	v_lshl_add_u64 v[228:229], v[236:237], 0, s[34:35]
	s_mov_b32 m0, s90
	s_nop 0
	global_load_lds_dwordx4 v[228:229], off
	v_lshl_add_u64 v[228:229], v[238:239], 0, s[34:35]
	s_mov_b32 m0, s91
	s_nop 0
	global_load_lds_dwordx4 v[228:229], off
	ds_read_b128 v[196:199], v148 offset:49152
	ds_read_b128 v[200:203], v148 offset:50176
	ds_read_b128 v[204:207], v148 offset:51200
	ds_read_b128 v[208:211], v148 offset:52224
	ds_read_b128 v[212:215], v148 offset:53248
	ds_read_b128 v[216:219], v148 offset:54272
	ds_read_b128 v[220:223], v148 offset:55296
	ds_read_b128 v[224:227], v148 offset:56320
	s_waitcnt vmcnt(8)
	s_waitcnt lgkmcnt(0)
	s_barrier
	v_mfma_f32_16x16x32_bf16 v[62:65], v[142:145], v[196:199], v[62:65]
	v_mfma_f32_16x16x32_bf16 v[58:61], v[154:157], v[196:199], v[58:61]
	v_mfma_f32_16x16x32_bf16 v[46:49], v[142:145], v[204:207], v[46:49]
	v_mfma_f32_16x16x32_bf16 v[42:45], v[154:157], v[204:207], v[42:45]
	v_mfma_f32_16x16x32_bf16 v[28:31], v[142:145], v[212:215], v[28:31]
	v_mfma_f32_16x16x32_bf16 v[24:27], v[154:157], v[212:215], v[24:27]
	v_mfma_f32_16x16x32_bf16 v[12:15], v[142:145], v[220:223], v[12:15]
	v_mfma_f32_16x16x32_bf16 v[8:11], v[154:157], v[220:223], v[8:11]
	v_mfma_f32_16x16x32_bf16 v[62:65], v[150:153], v[200:203], v[62:65]
	v_mfma_f32_16x16x32_bf16 v[58:61], v[158:161], v[200:203], v[58:61]
	v_mfma_f32_16x16x32_bf16 v[46:49], v[150:153], v[208:211], v[46:49]
	v_mfma_f32_16x16x32_bf16 v[42:45], v[158:161], v[208:211], v[42:45]
	v_mfma_f32_16x16x32_bf16 v[28:31], v[150:153], v[216:219], v[28:31]
	v_mfma_f32_16x16x32_bf16 v[24:27], v[158:161], v[216:219], v[24:27]
	v_mfma_f32_16x16x32_bf16 v[12:15], v[150:153], v[224:227], v[12:15]
	v_mfma_f32_16x16x32_bf16 v[8:11], v[158:161], v[224:227], v[8:11]
	v_mfma_f32_16x16x32_bf16 v[54:57], v[170:173], v[196:199], v[54:57]
	v_mfma_f32_16x16x32_bf16 v[50:53], v[178:181], v[196:199], v[50:53]
	v_mfma_f32_16x16x32_bf16 v[38:41], v[170:173], v[204:207], v[38:41]
	v_mfma_f32_16x16x32_bf16 v[34:37], v[178:181], v[204:207], v[34:37]
	v_mfma_f32_16x16x32_bf16 v[20:23], v[170:173], v[212:215], v[20:23]
	v_mfma_f32_16x16x32_bf16 v[16:19], v[178:181], v[212:215], v[16:19]
	v_mfma_f32_16x16x32_bf16 v[4:7], v[170:173], v[220:223], v[4:7]
	v_mfma_f32_16x16x32_bf16 v[0:3], v[178:181], v[220:223], v[0:3]
	v_mfma_f32_16x16x32_bf16 v[54:57], v[174:177], v[200:203], v[54:57]
	v_mfma_f32_16x16x32_bf16 v[50:53], v[182:185], v[200:203], v[50:53]
	v_mfma_f32_16x16x32_bf16 v[38:41], v[174:177], v[208:211], v[38:41]
	v_mfma_f32_16x16x32_bf16 v[34:37], v[182:185], v[208:211], v[34:37]
	v_mfma_f32_16x16x32_bf16 v[20:23], v[174:177], v[216:219], v[20:23]
	v_mfma_f32_16x16x32_bf16 v[16:19], v[182:185], v[216:219], v[16:19]
	v_mfma_f32_16x16x32_bf16 v[4:7], v[174:177], v[224:227], v[4:7]
	v_mfma_f32_16x16x32_bf16 v[0:3], v[182:185], v[224:227], v[0:3]
	s_barrier
	s_add_u32 s48, s48, 0x100
	s_addc_u32 s49, s49, 0
	s_add_u32 s44, s44, 0x100
	s_addc_u32 s45, s45, 0
	s_cmp_ge_u32 vcc_lo, s85
	s_mov_b32 s46, vcc_lo
	s_cbranch_scc0 .LBB0_411
	s_and_b64 vcc, exec, s[42:43]
	s_cbranch_vccz .LBB0_414
	s_barrier

; #define PG8_STAGE(bufoff, gbase, voff) do { _Pragma("unroll") for (int _i = 0; _i < 2; ++_i) \
;         __builtin_amdgcn_global_load_lds((const unsigned*)((const char*)(gbase) + (voff)[_i]), (PG8_LAS unsigned*)(lds + (bufoff) + ldsw + _i * 8192), 16, 0, 0); } while (0)
; #define PG8_LDA(dst, b, h) do { _Pragma("unroll") for (int m = 0; m < 4; ++m) _Pragma("unroll") for (int k = 0; k < 2; ++k) dst[m][k] = *(const PG8_LAS bf16x8*)(lds + PG8_SA(b, h) + aoff + m * 2048 + k * 1024); } while (0)
; #define PG8_LDB(dst, b, h) do { _Pragma("unroll") for (int n = 0; n < 2; ++n) _Pragma("unroll") for (int k = 0; k < 2; ++k) dst[n][k] = *(const PG8_LAS bf16x8*)(lds + PG8_SB(b, h) + boff + n * 2048 + k * 1024); } while (0)
; #define PG8_MMA(ai, bj, At, Bt) do { __builtin_amdgcn_s_setprio(1); _Pragma("unroll") for (int m = 0; m < 4; ++m) _Pragma("unroll") for (int n = 0; n < 2; ++n) _Pragma("unroll") for (int k = 0; k < 2; ++k) \
;         acc[ai][bj][m][n] = __builtin_amdgcn_mfma_f32_16x16x32_bf16(Bt[n][k], At[m][k], acc[ai][bj][m][n], 0, 0, 0); __builtin_amdgcn_s_setprio(0); } while (0)
; #define PG8_WAIT_V(n) asm volatile("s_waitcnt vmcnt(" #n ")" ::: "memory")
; #define PG8_WAIT_L(n) asm volatile("s_waitcnt lgkmcnt(" #n ")" ::: "memory")
; #define PG8_BAR __builtin_amdgcn_s_barrier()
; #define PG8_SCHED __builtin_amdgcn_sched_barrier(0)
; template <class Epi, class Sched, bool ALIGN_EPI = false, bool SP2 = false>
; __device__ __forceinline__ void gemm_phase(PG8_LAS unsigned char* lds, const Gemm g, const Sched& S, const Epi& E) {
;     ...
;             PG8_LDB(B0, 0, 0); PG8_LDB(B1, 0, 1); PG8_SCHED; PG8_LDA(At, 0, 0); PG8_STAGE(PG8_SA(1, 1), a1 + hstep, voffA);
;             PG8_WAIT_V(8); PG8_WAIT_L(0); PG8_BAR; PG8_MMA(0, 0, At, B0); PG8_MMA(0, 1, At, B1); PG8_BAR; PG8_SCHED;
;             PG8_LDA(At, 0, 1); PG8_STAGE(PG8_SB(0, 0), b2, voffB); PG8_STAGE(PG8_SB(0, 1), b2 + hstep, voffB); PG8_STAGE(PG8_SA(0, 0), a2, voffA);
;             PG8_WAIT_V(8); PG8_WAIT_L(0); PG8_BAR; PG8_MMA(1, 0, At, B0); PG8_MMA(1, 1, At, B1); PG8_BAR; PG8_SCHED;
.LBB0_546:
	s_add_i32 s48, s46, 2
	s_add_u32 s49, s44, 0x80
	s_addc_u32 s47, s45, 0
	s_add_i32 s61, 0, 0x10000
	s_cmp_eq_u32 s87, s46
	s_cselect_b32 s47, s43, s47
	s_cselect_b32 s46, s42, s49
	s_cselect_b32 s93, s77, s9
	s_cselect_b32 s92, s76, s0
	s_add_i32 s49, 0, 0x14000
	v_lshl_add_u64 v[228:229], s[44:45], 0, v[140:141]
	s_add_i32 m0, s78, 0xc000
	s_nop 0
	global_load_lds_dwordx4 v[228:229], off
	v_lshl_add_u64 v[228:229], s[44:45], 0, v[138:139]
	s_add_i32 m0, s78, 0xe000
	s_nop 0
	global_load_lds_dwordx4 v[228:229], off
	v_add_u32_e32 v149, s61, v146
	ds_read_b128 v[142:145], v149
	ds_read_b128 v[150:153], v149 offset:1024
	ds_read_b128 v[154:157], v149 offset:2048
	ds_read_b128 v[158:161], v149 offset:3072
	v_add_u32_e32 v149, s49, v146
	ds_read_b128 v[170:173], v149
	ds_read_b128 v[174:177], v149 offset:1024
	ds_read_b128 v[178:181], v149 offset:2048
	ds_read_b128 v[182:185], v149 offset:3072
	ds_read_b128 v[196:199], v148
	ds_read_b128 v[200:203], v148 offset:1024
	ds_read_b128 v[204:207], v148 offset:2048
	ds_read_b128 v[208:211], v148 offset:3072
	ds_read_b128 v[212:215], v148 offset:4096
	ds_read_b128 v[216:219], v148 offset:5120
	ds_read_b128 v[220:223], v148 offset:6144
	ds_read_b128 v[224:227], v148 offset:7168
	s_waitcnt vmcnt(8)
	s_waitcnt lgkmcnt(0)
	s_barrier
	v_mfma_f32_16x16x32_bf16 v[126:129], v[142:145], v[196:199], v[126:129]
	v_mfma_f32_16x16x32_bf16 v[122:125], v[154:157], v[196:199], v[122:125]
	v_mfma_f32_16x16x32_bf16 v[110:113], v[142:145], v[204:207], v[110:113]
	v_mfma_f32_16x16x32_bf16 v[106:109], v[154:157], v[204:207], v[106:109]
	v_mfma_f32_16x16x32_bf16 v[94:97], v[142:145], v[212:215], v[94:97]
	v_mfma_f32_16x16x32_bf16 v[90:93], v[154:157], v[212:215], v[90:93]
	v_mfma_f32_16x16x32_bf16 v[78:81], v[142:145], v[220:223], v[78:81]
	v_mfma_f32_16x16x32_bf16 v[74:77], v[154:157], v[220:223], v[74:77]
	v_mfma_f32_16x16x32_bf16 v[126:129], v[150:153], v[200:203], v[126:129]
	v_mfma_f32_16x16x32_bf16 v[122:125], v[158:161], v[200:203], v[122:125]
	v_mfma_f32_16x16x32_bf16 v[110:113], v[150:153], v[208:211], v[110:113]
	v_mfma_f32_16x16x32_bf16 v[106:109], v[158:161], v[208:211], v[106:109]
	v_mfma_f32_16x16x32_bf16 v[94:97], v[150:153], v[216:219], v[94:97]
	v_mfma_f32_16x16x32_bf16 v[90:93], v[158:161], v[216:219], v[90:93]
	v_mfma_f32_16x16x32_bf16 v[78:81], v[150:153], v[224:227], v[78:81]
	v_mfma_f32_16x16x32_bf16 v[74:77], v[158:161], v[224:227], v[74:77]
	v_mfma_f32_16x16x32_bf16 v[118:121], v[170:173], v[196:199], v[118:121]
	v_mfma_f32_16x16x32_bf16 v[114:117], v[178:181], v[196:199], v[114:117]
	v_mfma_f32_16x16x32_bf16 v[102:105], v[170:173], v[204:207], v[102:105]
	v_mfma_f32_16x16x32_bf16 v[98:101], v[178:181], v[204:207], v[98:101]
	v_mfma_f32_16x16x32_bf16 v[86:89], v[170:173], v[212:215], v[86:89]
	v_mfma_f32_16x16x32_bf16 v[82:85], v[178:181], v[212:215], v[82:85]
	v_mfma_f32_16x16x32_bf16 v[70:73], v[170:173], v[220:223], v[70:73]
	v_mfma_f32_16x16x32_bf16 v[66:69], v[178:181], v[220:223], v[66:69]
	v_mfma_f32_16x16x32_bf16 v[118:121], v[174:177], v[200:203], v[118:121]
	v_mfma_f32_16x16x32_bf16 v[114:117], v[182:185], v[200:203], v[114:117]
	v_mfma_f32_16x16x32_bf16 v[102:105], v[174:177], v[208:211], v[102:105]
	v_mfma_f32_16x16x32_bf16 v[98:101], v[182:185], v[208:211], v[98:101]
	v_mfma_f32_16x16x32_bf16 v[86:89], v[174:177], v[216:219], v[86:89]
	v_mfma_f32_16x16x32_bf16 v[82:85], v[182:185], v[216:219], v[82:85]
	v_mfma_f32_16x16x32_bf16 v[70:73], v[174:177], v[224:227], v[70:73]
	v_mfma_f32_16x16x32_bf16 v[66:69], v[182:185], v[224:227], v[66:69]
	s_barrier
	s_add_i32 s61, s61, s51
	v_lshl_add_u64 v[228:229], s[92:93], 0, v[132:133]
	s_mov_b32 m0, s61
	s_nop 0
	global_load_lds_dwordx4 v[228:229], off
	s_add_i32 m0, s61, 0x2000
	v_lshl_add_u64 v[230:231], s[92:93], 0, v[136:137]
	s_add_u32 s92, s92, s8
	s_addc_u32 s93, s93, 0
	s_add_i32 s49, s49, s51
	global_load_lds_dwordx4 v[230:231], off
	v_lshl_add_u64 v[232:233], s[92:93], 0, v[132:133]
	s_mov_b32 m0, s49
	v_lshl_add_u64 v[234:235], s[92:93], 0, v[136:137]
	global_load_lds_dwordx4 v[232:233], off
	s_add_i32 m0, s49, 0x2000
	v_lshl_add_u64 v[236:237], s[46:47], 0, v[130:131]
	global_load_lds_dwordx4 v[234:235], off
	s_mov_b32 m0, s78
	v_lshl_add_u64 v[238:239], s[46:47], 0, v[134:135]
	global_load_lds_dwordx4 v[236:237], off
	s_mov_b32 m0, s79
	s_nop 0
	global_load_lds_dwordx4 v[238:239], off
	ds_read_b128 v[196:199], v148 offset:16384
	ds_read_b128 v[200:203], v148 offset:17408
	ds_read_b128 v[204:207], v148 offset:18432
	ds_read_b128 v[208:211], v148 offset:19456
	ds_read_b128 v[212:215], v148 offset:20480
	ds_read_b128 v[216:219], v148 offset:21504
	ds_read_b128 v[220:223], v148 offset:22528
	ds_read_b128 v[224:227], v148 offset:23552
	s_waitcnt vmcnt(8)
	s_waitcnt lgkmcnt(0)
	s_barrier
; #define PG8_STAGE(bufoff, gbase, voff) do { _Pragma("unroll") for (int _i = 0; _i < 2; ++_i) \
;         __builtin_amdgcn_global_load_lds((const unsigned*)((const char*)(gbase) + (voff)[_i]), (PG8_LAS unsigned*)(lds + (bufoff) + ldsw + _i * 8192), 16, 0, 0); } while (0)
; #define PG8_LDA(dst, b, h) do { _Pragma("unroll") for (int m = 0; m < 4; ++m) _Pragma("unroll") for (int k = 0; k < 2; ++k) dst[m][k] = *(const PG8_LAS bf16x8*)(lds + PG8_SA(b, h) + aoff + m * 2048 + k * 1024); } while (0)
; #define PG8_LDB(dst, b, h) do { _Pragma("unroll") for (int n = 0; n < 2; ++n) _Pragma("unroll") for (int k = 0; k < 2; ++k) dst[n][k] = *(const PG8_LAS bf16x8*)(lds + PG8_SB(b, h) + boff + n * 2048 + k * 1024); } while (0)
; #define PG8_MMA(ai, bj, At, Bt) do { __builtin_amdgcn_s_setprio(1); _Pragma("unroll") for (int m = 0; m < 4; ++m) _Pragma("unroll") for (int n = 0; n < 2; ++n) _Pragma("unroll") for (int k = 0; k < 2; ++k) \
;         acc[ai][bj][m][n] = __builtin_amdgcn_mfma_f32_16x16x32_bf16(Bt[n][k], At[m][k], acc[ai][bj][m][n], 0, 0, 0); __builtin_amdgcn_s_setprio(0); } while (0)
; #define PG8_WAIT_V(n) asm volatile("s_waitcnt vmcnt(" #n ")" ::: "memory")
; #define PG8_WAIT_L(n) asm volatile("s_waitcnt lgkmcnt(" #n ")" ::: "memory")
; #define PG8_BAR __builtin_amdgcn_s_barrier()
; #define PG8_SCHED __builtin_amdgcn_sched_barrier(0)
; template <class Epi, class Sched, bool ALIGN_EPI = false, bool SP2 = false>
; __device__ __forceinline__ void gemm_phase(PG8_LAS unsigned char* lds, const Gemm g, const Sched& S, const Epi& E) {
;     ...
;             PG8_WAIT_V(8); PG8_WAIT_L(0); PG8_BAR; PG8_MMA(1, 0, At, B0); PG8_MMA(1, 1, At, B1); PG8_BAR; PG8_SCHED;
;             PG8_LDB(B0, 1, 0); PG8_LDB(B1, 1, 1); PG8_SCHED; PG8_LDA(At, 1, 0); PG8_STAGE(PG8_SA(0, 1), a2 + hstep, voffA);
;             PG8_WAIT_V(8); PG8_WAIT_L(0); PG8_BAR; PG8_MMA(0, 0, At, B0); PG8_MMA(0, 1, At, B1); PG8_BAR; PG8_SCHED;
	v_mfma_f32_16x16x32_bf16 v[62:65], v[142:145], v[196:199], v[62:65]
	v_mfma_f32_16x16x32_bf16 v[58:61], v[154:157], v[196:199], v[58:61]
	v_mfma_f32_16x16x32_bf16 v[46:49], v[142:145], v[204:207], v[46:49]
	v_mfma_f32_16x16x32_bf16 v[42:45], v[154:157], v[204:207], v[42:45]
	v_mfma_f32_16x16x32_bf16 v[28:31], v[142:145], v[212:215], v[28:31]
	v_mfma_f32_16x16x32_bf16 v[24:27], v[154:157], v[212:215], v[24:27]
	v_mfma_f32_16x16x32_bf16 v[12:15], v[142:145], v[220:223], v[12:15]
	v_mfma_f32_16x16x32_bf16 v[8:11], v[154:157], v[220:223], v[8:11]
	v_mfma_f32_16x16x32_bf16 v[62:65], v[150:153], v[200:203], v[62:65]
	v_mfma_f32_16x16x32_bf16 v[58:61], v[158:161], v[200:203], v[58:61]
	v_mfma_f32_16x16x32_bf16 v[46:49], v[150:153], v[208:211], v[46:49]
	v_mfma_f32_16x16x32_bf16 v[42:45], v[158:161], v[208:211], v[42:45]
	v_mfma_f32_16x16x32_bf16 v[28:31], v[150:153], v[216:219], v[28:31]
	v_mfma_f32_16x16x32_bf16 v[24:27], v[158:161], v[216:219], v[24:27]
	v_mfma_f32_16x16x32_bf16 v[12:15], v[150:153], v[224:227], v[12:15]
	v_mfma_f32_16x16x32_bf16 v[8:11], v[158:161], v[224:227], v[8:11]
	v_mfma_f32_16x16x32_bf16 v[54:57], v[170:173], v[196:199], v[54:57]
	v_mfma_f32_16x16x32_bf16 v[50:53], v[178:181], v[196:199], v[50:53]
	v_mfma_f32_16x16x32_bf16 v[38:41], v[170:173], v[204:207], v[38:41]
	v_mfma_f32_16x16x32_bf16 v[34:37], v[178:181], v[204:207], v[34:37]
	v_mfma_f32_16x16x32_bf16 v[20:23], v[170:173], v[212:215], v[20:23]
	v_mfma_f32_16x16x32_bf16 v[16:19], v[178:181], v[212:215], v[16:19]
	v_mfma_f32_16x16x32_bf16 v[4:7], v[170:173], v[220:223], v[4:7]
	v_mfma_f32_16x16x32_bf16 v[0:3], v[178:181], v[220:223], v[0:3]
	v_mfma_f32_16x16x32_bf16 v[54:57], v[174:177], v[200:203], v[54:57]
	v_mfma_f32_16x16x32_bf16 v[50:53], v[182:185], v[200:203], v[50:53]
	v_mfma_f32_16x16x32_bf16 v[38:41], v[174:177], v[208:211], v[38:41]
	v_mfma_f32_16x16x32_bf16 v[34:37], v[182:185], v[208:211], v[34:37]
	v_mfma_f32_16x16x32_bf16 v[20:23], v[174:177], v[216:219], v[20:23]
	v_mfma_f32_16x16x32_bf16 v[16:19], v[182:185], v[216:219], v[16:19]
	v_mfma_f32_16x16x32_bf16 v[4:7], v[174:177], v[224:227], v[4:7]
	v_mfma_f32_16x16x32_bf16 v[0:3], v[182:185], v[224:227], v[0:3]
	s_barrier
	s_add_i32 s49, 0, 0x18000
	s_add_i32 s61, 0, 0x1c000
	s_add_u32 s46, s46, s8
	s_addc_u32 s47, s47, 0
	s_mov_b32 m0, s80
	v_lshl_add_u64 v[240:241], s[46:47], 0, v[130:131]
	global_load_lds_dwordx4 v[240:241], off
	v_lshl_add_u64 v[240:241], s[46:47], 0, v[134:135]
	s_mov_b32 m0, s81
	s_nop 0
	global_load_lds_dwordx4 v[240:241], off
	v_add_u32_e32 v149, s49, v146
	ds_read_b128 v[142:145], v149
	ds_read_b128 v[150:153], v149 offset:1024
	ds_read_b128 v[154:157], v149 offset:2048
	ds_read_b128 v[158:161], v149 offset:3072
	v_add_u32_e32 v149, s61, v146
	ds_read_b128 v[170:173], v149
	ds_read_b128 v[174:177], v149 offset:1024
	ds_read_b128 v[178:181], v149 offset:2048
	ds_read_b128 v[182:185], v149 offset:3072
	ds_read_b128 v[196:199], v148 offset:32768
	ds_read_b128 v[200:203], v148 offset:33792
	ds_read_b128 v[204:207], v148 offset:34816
	ds_read_b128 v[208:211], v148 offset:35840
	ds_read_b128 v[212:215], v148 offset:36864
	ds_read_b128 v[216:219], v148 offset:37888
	ds_read_b128 v[220:223], v148 offset:38912
	ds_read_b128 v[224:227], v148 offset:39936
	s_waitcnt vmcnt(8)
	s_waitcnt lgkmcnt(0)
	s_barrier
	v_mfma_f32_16x16x32_bf16 v[126:129], v[142:145], v[196:199], v[126:129]
	v_mfma_f32_16x16x32_bf16 v[122:125], v[154:157], v[196:199], v[122:125]
	v_mfma_f32_16x16x32_bf16 v[110:113], v[142:145], v[204:207], v[110:113]
	v_mfma_f32_16x16x32_bf16 v[106:109], v[154:157], v[204:207], v[106:109]
	v_mfma_f32_16x16x32_bf16 v[94:97], v[142:145], v[212:215], v[94:97]
	v_mfma_f32_16x16x32_bf16 v[90:93], v[154:157], v[212:215], v[90:93]
	v_mfma_f32_16x16x32_bf16 v[78:81], v[142:145], v[220:223], v[78:81]
	v_mfma_f32_16x16x32_bf16 v[74:77], v[154:157], v[220:223], v[74:77]
	v_mfma_f32_16x16x32_bf16 v[126:129], v[150:153], v[200:203], v[126:129]
	v_mfma_f32_16x16x32_bf16 v[122:125], v[158:161], v[200:203], v[122:125]
	v_mfma_f32_16x16x32_bf16 v[110:113], v[150:153], v[208:211], v[110:113]
	v_mfma_f32_16x16x32_bf16 v[106:109], v[158:161], v[208:211], v[106:109]
	v_mfma_f32_16x16x32_bf16 v[94:97], v[150:153], v[216:219], v[94:97]
	v_mfma_f32_16x16x32_bf16 v[90:93], v[158:161], v[216:219], v[90:93]
	v_mfma_f32_16x16x32_bf16 v[78:81], v[150:153], v[224:227], v[78:81]
	v_mfma_f32_16x16x32_bf16 v[74:77], v[158:161], v[224:227], v[74:77]
	v_mfma_f32_16x16x32_bf16 v[118:121], v[170:173], v[196:199], v[118:121]
	v_mfma_f32_16x16x32_bf16 v[114:117], v[178:181], v[196:199], v[114:117]
	v_mfma_f32_16x16x32_bf16 v[102:105], v[170:173], v[204:207], v[102:105]
	v_mfma_f32_16x16x32_bf16 v[98:101], v[178:181], v[204:207], v[98:101]
	v_mfma_f32_16x16x32_bf16 v[86:89], v[170:173], v[212:215], v[86:89]
	v_mfma_f32_16x16x32_bf16 v[82:85], v[178:181], v[212:215], v[82:85]
	v_mfma_f32_16x16x32_bf16 v[70:73], v[170:173], v[220:223], v[70:73]
	v_mfma_f32_16x16x32_bf16 v[66:69], v[178:181], v[220:223], v[66:69]
	v_mfma_f32_16x16x32_bf16 v[118:121], v[174:177], v[200:203], v[118:121]
	v_mfma_f32_16x16x32_bf16 v[114:117], v[182:185], v[200:203], v[114:117]
	v_mfma_f32_16x16x32_bf16 v[102:105], v[174:177], v[208:211], v[102:105]
	v_mfma_f32_16x16x32_bf16 v[98:101], v[182:185], v[208:211], v[98:101]
	v_mfma_f32_16x16x32_bf16 v[86:89], v[174:177], v[216:219], v[86:89]
	v_mfma_f32_16x16x32_bf16 v[82:85], v[182:185], v[216:219], v[82:85]
	v_mfma_f32_16x16x32_bf16 v[70:73], v[174:177], v[224:227], v[70:73]
	v_mfma_f32_16x16x32_bf16 v[66:69], v[182:185], v[224:227], v[66:69]
	s_barrier
; #define PG8_STAGE(bufoff, gbase, voff) do { _Pragma("unroll") for (int _i = 0; _i < 2; ++_i) \
;         __builtin_amdgcn_global_load_lds((const unsigned*)((const char*)(gbase) + (voff)[_i]), (PG8_LAS unsigned*)(lds + (bufoff) + ldsw + _i * 8192), 16, 0, 0); } while (0)
; #define PG8_LDA(dst, b, h) do { _Pragma("unroll") for (int m = 0; m < 4; ++m) _Pragma("unroll") for (int k = 0; k < 2; ++k) dst[m][k] = *(const PG8_LAS bf16x8*)(lds + PG8_SA(b, h) + aoff + m * 2048 + k * 1024); } while (0)
; #define PG8_MMA(ai, bj, At, Bt) do { __builtin_amdgcn_s_setprio(1); _Pragma("unroll") for (int m = 0; m < 4; ++m) _Pragma("unroll") for (int n = 0; n < 2; ++n) _Pragma("unroll") for (int k = 0; k < 2; ++k) \
;         acc[ai][bj][m][n] = __builtin_amdgcn_mfma_f32_16x16x32_bf16(Bt[n][k], At[m][k], acc[ai][bj][m][n], 0, 0, 0); __builtin_amdgcn_s_setprio(0); } while (0)
; #define PG8_WAIT_V(n) asm volatile("s_waitcnt vmcnt(" #n ")" ::: "memory")
; #define PG8_WAIT_L(n) asm volatile("s_waitcnt lgkmcnt(" #n ")" ::: "memory")
; #define PG8_BAR __builtin_amdgcn_s_barrier()
; #define PG8_SCHED __builtin_amdgcn_sched_barrier(0)
; template <class Epi, class Sched, bool ALIGN_EPI = false, bool SP2 = false>
; __device__ __forceinline__ void gemm_phase(PG8_LAS unsigned char* lds, const Gemm g, const Sched& S, const Epi& E) {
;     ...
;             PG8_LDA(At, 1, 1); PG8_STAGE(PG8_SB(1, 0), b3, voffB); PG8_STAGE(PG8_SB(1, 1), b3 + hstep, voffB); PG8_STAGE(PG8_SA(1, 0), a3, voffA);
;             PG8_WAIT_V(8); PG8_WAIT_L(0); PG8_BAR; PG8_MMA(1, 0, At, B0); PG8_MMA(1, 1, At, B1); PG8_BAR; PG8_SCHED;
;     ...
;         if constexpr (ALIGN_EPI) { if (wr == 0) PG8_BAR; }
	s_add_i32 s46, s49, s51
	v_lshl_add_u64 v[228:229], v[228:229], 0, s[34:35]
	s_mov_b32 m0, s46
	s_nop 0
	global_load_lds_dwordx4 v[228:229], off
	v_lshl_add_u64 v[228:229], v[230:231], 0, s[34:35]
	s_add_i32 m0, s46, 0x2000
	s_add_i32 s46, s61, s51
	global_load_lds_dwordx4 v[228:229], off
	v_lshl_add_u64 v[228:229], v[232:233], 0, s[34:35]
	s_mov_b32 m0, s46
	s_nop 0
	global_load_lds_dwordx4 v[228:229], off
	v_lshl_add_u64 v[228:229], v[234:235], 0, s[34:35]
	s_add_i32 m0, s46, 0x2000
	s_nop 0
	global_load_lds_dwordx4 v[228:229], off
	v_lshl_add_u64 v[228:229], v[236:237], 0, s[34:35]
	s_mov_b32 m0, s83
	s_nop 0
	global_load_lds_dwordx4 v[228:229], off
	v_lshl_add_u64 v[228:229], v[238:239], 0, s[34:35]
	s_mov_b32 m0, s84
	s_nop 0
	global_load_lds_dwordx4 v[228:229], off
	ds_read_b128 v[196:199], v148 offset:49152
	ds_read_b128 v[200:203], v148 offset:50176
	ds_read_b128 v[204:207], v148 offset:51200
	ds_read_b128 v[208:211], v148 offset:52224
	ds_read_b128 v[212:215], v148 offset:53248
	ds_read_b128 v[216:219], v148 offset:54272
	ds_read_b128 v[220:223], v148 offset:55296
	ds_read_b128 v[224:227], v148 offset:56320
	s_waitcnt vmcnt(8)
	s_waitcnt lgkmcnt(0)
	s_barrier
	v_mfma_f32_16x16x32_bf16 v[62:65], v[142:145], v[196:199], v[62:65]
	v_mfma_f32_16x16x32_bf16 v[58:61], v[154:157], v[196:199], v[58:61]
	v_mfma_f32_16x16x32_bf16 v[46:49], v[142:145], v[204:207], v[46:49]
	v_mfma_f32_16x16x32_bf16 v[42:45], v[154:157], v[204:207], v[42:45]
	v_mfma_f32_16x16x32_bf16 v[28:31], v[142:145], v[212:215], v[28:31]
	v_mfma_f32_16x16x32_bf16 v[24:27], v[154:157], v[212:215], v[24:27]
	v_mfma_f32_16x16x32_bf16 v[12:15], v[142:145], v[220:223], v[12:15]
	v_mfma_f32_16x16x32_bf16 v[8:11], v[154:157], v[220:223], v[8:11]
	v_mfma_f32_16x16x32_bf16 v[62:65], v[150:153], v[200:203], v[62:65]
	v_mfma_f32_16x16x32_bf16 v[58:61], v[158:161], v[200:203], v[58:61]
	v_mfma_f32_16x16x32_bf16 v[46:49], v[150:153], v[208:211], v[46:49]
	v_mfma_f32_16x16x32_bf16 v[42:45], v[158:161], v[208:211], v[42:45]
	v_mfma_f32_16x16x32_bf16 v[28:31], v[150:153], v[216:219], v[28:31]
	v_mfma_f32_16x16x32_bf16 v[24:27], v[158:161], v[216:219], v[24:27]
	v_mfma_f32_16x16x32_bf16 v[12:15], v[150:153], v[224:227], v[12:15]
	v_mfma_f32_16x16x32_bf16 v[8:11], v[158:161], v[224:227], v[8:11]
	v_mfma_f32_16x16x32_bf16 v[54:57], v[170:173], v[196:199], v[54:57]
	v_mfma_f32_16x16x32_bf16 v[50:53], v[178:181], v[196:199], v[50:53]
	v_mfma_f32_16x16x32_bf16 v[38:41], v[170:173], v[204:207], v[38:41]
	v_mfma_f32_16x16x32_bf16 v[34:37], v[178:181], v[204:207], v[34:37]
	v_mfma_f32_16x16x32_bf16 v[20:23], v[170:173], v[212:215], v[20:23]
	v_mfma_f32_16x16x32_bf16 v[16:19], v[178:181], v[212:215], v[16:19]
	v_mfma_f32_16x16x32_bf16 v[4:7], v[170:173], v[220:223], v[4:7]
	v_mfma_f32_16x16x32_bf16 v[0:3], v[178:181], v[220:223], v[0:3]
	v_mfma_f32_16x16x32_bf16 v[54:57], v[174:177], v[200:203], v[54:57]
	v_mfma_f32_16x16x32_bf16 v[50:53], v[182:185], v[200:203], v[50:53]
	v_mfma_f32_16x16x32_bf16 v[38:41], v[174:177], v[208:211], v[38:41]
	v_mfma_f32_16x16x32_bf16 v[34:37], v[182:185], v[208:211], v[34:37]
	v_mfma_f32_16x16x32_bf16 v[20:23], v[174:177], v[216:219], v[20:23]
	v_mfma_f32_16x16x32_bf16 v[16:19], v[182:185], v[216:219], v[16:19]
	v_mfma_f32_16x16x32_bf16 v[4:7], v[174:177], v[224:227], v[4:7]
	v_mfma_f32_16x16x32_bf16 v[0:3], v[182:185], v[224:227], v[0:3]
	s_barrier
	s_add_u32 s0, s0, 0x100
	s_addc_u32 s9, s9, 0
	s_add_u32 s44, s44, 0x100
	s_addc_u32 s45, s45, 0
	s_cmp_ge_u32 s48, s85
	s_mov_b32 s46, s48
	s_cbranch_scc0 .LBB0_546
	s_and_b64 vcc, exec, s[40:41]
	s_cbranch_vccz .LBB0_549
	s_barrier
